# P1 cumsum: the 16 per-thread F2 dword stores issued as 4 dwordx4 stores
# speedup vs baseline: 1.0063x; 1.0063x over previous
; __device__ __forceinline__ unsigned f2bf(float f) { unsigned u = __builtin_bit_cast(unsigned, f); return (u + 0x7fffu + ((u >> 16) & 1u)) >> 16; }
; __global__ void __launch_bounds__(NWAVES * 64, 2) fwd_megakernel(Args args) {
;     ...
;             float* dst = F2 + (size_t)bh * SEQ + tid * 16;
; #pragma unroll
;             for (int i = 0; i < 16; ++i) { const float f = (base + loc[i]) * LOG2E; dst[i] = f;
;                 const float nf = -f; const unsigned h1 = f2bf(nf); const float r1 = nf - __builtin_bit_cast(float, h1 << 16); const unsigned h2 = f2bf(r1); const float r2 = r1 - __builtin_bit_cast(float, h2 << 16); const unsigned h3 = f2bf(r2);
;                 v4u o; o.x = h1 | (h2 << 16); o.y = h3; o.z = 0u; o.w = 0u; *(v4u*)(FS3 + ((size_t)bh * SEQ + tid * 16 + i) * 8) = o; }
.LBB0_232:
	s_ashr_i32 s11, s10, 31
	s_lshl_b64 s[34:35], s[10:11], 15
	v_add_f32_e32 v2, v22, v2
	v_lshl_add_u64 v[8:9], v[6:7], 0, s[34:35]
	v_mul_f32_e32 v3, 0x3fb8aa3b, v2
	v_mov_b32_e32 v240, v3
	v_xor_b32_e32 v3, 0x80000000, v3
	v_bfe_u32 v5, v3, 16, 1
	v_add3_u32 v5, v3, v5, s31
	v_and_b32_e32 v3, 0xffff0000, v5
	v_fma_f32 v2, v2, s33, -v3
	v_bfe_u32 v3, v2, 16, 1
	v_add3_u32 v3, v2, v3, s31
	v_and_b32_e32 v35, 0xffff0000, v3
	v_sub_f32_e32 v2, v2, v35
	s_lshl_b64 s[26:27], s[10:11], 13
	v_bfe_u32 v3, v2, 16, 1
	v_lshl_add_u64 v[10:11], s[26:27], 0, v[130:131]
	v_add3_u32 v2, v2, v3, s31
	v_lshrrev_b32_e32 v3, 16, v2
	v_or_b32_sdwa v2, v35, v5 dst_sel:DWORD dst_unused:UNUSED_PAD src0_sel:DWORD src1_sel:WORD_1
	v_mov_b32_e32 v5, v4
	v_lshl_add_u64 v[10:11], v[10:11], 4, s[74:75]
	global_store_dwordx4 v[10:11], v[2:5], off
	s_add_i32 s10, s10, s90
	s_cmp_gt_i32 s10, 31
	v_add_f32_e32 v2, v22, v34
	v_mul_f32_e32 v3, 0x3fb8aa3b, v2
	v_mov_b32_e32 v241, v3
	v_xor_b32_e32 v3, 0x80000000, v3
	v_bfe_u32 v5, v3, 16, 1
	v_add3_u32 v5, v3, v5, s31
	v_and_b32_e32 v3, 0xffff0000, v5
	v_fma_f32 v2, v2, s33, -v3
	v_bfe_u32 v3, v2, 16, 1
	v_add3_u32 v3, v2, v3, s31
	v_and_b32_e32 v34, 0xffff0000, v3
	v_sub_f32_e32 v2, v2, v34
	v_bfe_u32 v3, v2, 16, 1
	v_add3_u32 v2, v2, v3, s31
	v_lshrrev_b32_e32 v3, 16, v2
	v_or_b32_sdwa v2, v34, v5 dst_sel:DWORD dst_unused:UNUSED_PAD src0_sel:DWORD src1_sel:WORD_1
	v_mov_b32_e32 v5, v4
	global_store_dwordx4 v[10:11], v[2:5], off offset:16
	s_nop 1
	v_add_f32_e32 v2, v22, v33
	v_mul_f32_e32 v3, 0x3fb8aa3b, v2
	v_mov_b32_e32 v242, v3
	v_xor_b32_e32 v3, 0x80000000, v3
	v_bfe_u32 v5, v3, 16, 1
	v_add3_u32 v5, v3, v5, s31
	v_and_b32_e32 v3, 0xffff0000, v5
	v_fma_f32 v2, v2, s33, -v3
	v_bfe_u32 v3, v2, 16, 1
	v_add3_u32 v3, v2, v3, s31
	v_and_b32_e32 v33, 0xffff0000, v3
	v_sub_f32_e32 v2, v2, v33
	v_bfe_u32 v3, v2, 16, 1
	v_add3_u32 v2, v2, v3, s31
	v_lshrrev_b32_e32 v3, 16, v2
	v_or_b32_sdwa v2, v33, v5 dst_sel:DWORD dst_unused:UNUSED_PAD src0_sel:DWORD src1_sel:WORD_1
	v_mov_b32_e32 v5, v4
	global_store_dwordx4 v[10:11], v[2:5], off offset:32
	s_nop 1
	v_add_f32_e32 v2, v22, v32
	v_mul_f32_e32 v3, 0x3fb8aa3b, v2
	v_mov_b32_e32 v243, v3
	global_store_dwordx4 v[8:9], v[240:243], off
	v_xor_b32_e32 v3, 0x80000000, v3
	v_bfe_u32 v5, v3, 16, 1
	v_add3_u32 v5, v3, v5, s31
	v_and_b32_e32 v3, 0xffff0000, v5
	v_fma_f32 v2, v2, s33, -v3
	v_bfe_u32 v3, v2, 16, 1
	v_add3_u32 v3, v2, v3, s31
	v_and_b32_e32 v32, 0xffff0000, v3
	v_sub_f32_e32 v2, v2, v32
	v_bfe_u32 v3, v2, 16, 1
	v_add3_u32 v2, v2, v3, s31
	v_lshrrev_b32_e32 v3, 16, v2
	v_or_b32_sdwa v2, v32, v5 dst_sel:DWORD dst_unused:UNUSED_PAD src0_sel:DWORD src1_sel:WORD_1
	v_mov_b32_e32 v5, v4
	global_store_dwordx4 v[10:11], v[2:5], off offset:48
	s_nop 1
	v_add_f32_e32 v2, v22, v31
	v_mul_f32_e32 v3, 0x3fb8aa3b, v2
	v_mov_b32_e32 v244, v3
	v_xor_b32_e32 v3, 0x80000000, v3
	v_bfe_u32 v5, v3, 16, 1
	v_add3_u32 v5, v3, v5, s31
	v_and_b32_e32 v3, 0xffff0000, v5
	v_fma_f32 v2, v2, s33, -v3
	v_bfe_u32 v3, v2, 16, 1
	v_add3_u32 v3, v2, v3, s31
	v_and_b32_e32 v31, 0xffff0000, v3
	v_sub_f32_e32 v2, v2, v31
	v_bfe_u32 v3, v2, 16, 1
	v_add3_u32 v2, v2, v3, s31
	v_lshrrev_b32_e32 v3, 16, v2
	v_or_b32_sdwa v2, v31, v5 dst_sel:DWORD dst_unused:UNUSED_PAD src0_sel:DWORD src1_sel:WORD_1
	v_mov_b32_e32 v5, v4
	global_store_dwordx4 v[10:11], v[2:5], off offset:64
	s_nop 1
	v_add_f32_e32 v2, v22, v30
	v_mul_f32_e32 v3, 0x3fb8aa3b, v2
	v_mov_b32_e32 v245, v3
	v_xor_b32_e32 v3, 0x80000000, v3
	v_bfe_u32 v5, v3, 16, 1
	v_add3_u32 v5, v3, v5, s31
	v_and_b32_e32 v3, 0xffff0000, v5
	v_fma_f32 v2, v2, s33, -v3
	v_bfe_u32 v3, v2, 16, 1
	v_add3_u32 v3, v2, v3, s31
	v_and_b32_e32 v30, 0xffff0000, v3
	v_sub_f32_e32 v2, v2, v30
	v_bfe_u32 v3, v2, 16, 1
	v_add3_u32 v2, v2, v3, s31
	v_lshrrev_b32_e32 v3, 16, v2
	v_or_b32_sdwa v2, v30, v5 dst_sel:DWORD dst_unused:UNUSED_PAD src0_sel:DWORD src1_sel:WORD_1
	v_mov_b32_e32 v5, v4
	global_store_dwordx4 v[10:11], v[2:5], off offset:80
	s_nop 1
	v_add_f32_e32 v2, v22, v29
	v_mul_f32_e32 v3, 0x3fb8aa3b, v2
	v_mov_b32_e32 v246, v3
	v_xor_b32_e32 v3, 0x80000000, v3
	v_bfe_u32 v5, v3, 16, 1
	v_add3_u32 v5, v3, v5, s31
	v_and_b32_e32 v3, 0xffff0000, v5
	v_fma_f32 v2, v2, s33, -v3
	v_bfe_u32 v3, v2, 16, 1
	v_add3_u32 v3, v2, v3, s31
	v_and_b32_e32 v29, 0xffff0000, v3
	v_sub_f32_e32 v2, v2, v29
	v_bfe_u32 v3, v2, 16, 1
	v_add3_u32 v2, v2, v3, s31
	v_lshrrev_b32_e32 v3, 16, v2
	v_or_b32_sdwa v2, v29, v5 dst_sel:DWORD dst_unused:UNUSED_PAD src0_sel:DWORD src1_sel:WORD_1
	v_mov_b32_e32 v5, v4
	global_store_dwordx4 v[10:11], v[2:5], off offset:96
	s_nop 1
	v_add_f32_e32 v2, v22, v28
	v_mul_f32_e32 v3, 0x3fb8aa3b, v2
	v_mov_b32_e32 v247, v3
	global_store_dwordx4 v[8:9], v[244:247], off offset:16
	v_xor_b32_e32 v3, 0x80000000, v3
	v_bfe_u32 v5, v3, 16, 1
	v_add3_u32 v5, v3, v5, s31
	v_and_b32_e32 v3, 0xffff0000, v5
	v_fma_f32 v2, v2, s33, -v3
	v_bfe_u32 v3, v2, 16, 1
	v_add3_u32 v3, v2, v3, s31
	v_and_b32_e32 v28, 0xffff0000, v3
	v_sub_f32_e32 v2, v2, v28
	v_bfe_u32 v3, v2, 16, 1
	v_add3_u32 v2, v2, v3, s31
	v_lshrrev_b32_e32 v3, 16, v2
	v_or_b32_sdwa v2, v28, v5 dst_sel:DWORD dst_unused:UNUSED_PAD src0_sel:DWORD src1_sel:WORD_1
; __device__ __forceinline__ unsigned f2bf(float f) { unsigned u = __builtin_bit_cast(unsigned, f); return (u + 0x7fffu + ((u >> 16) & 1u)) >> 16; }
; __global__ void __launch_bounds__(NWAVES * 64, 2) fwd_megakernel(Args args) {
;     ...
;             float* dst = F2 + (size_t)bh * SEQ + tid * 16;
; #pragma unroll
;             for (int i = 0; i < 16; ++i) { const float f = (base + loc[i]) * LOG2E; dst[i] = f;
;                 const float nf = -f; const unsigned h1 = f2bf(nf); const float r1 = nf - __builtin_bit_cast(float, h1 << 16); const unsigned h2 = f2bf(r1); const float r2 = r1 - __builtin_bit_cast(float, h2 << 16); const unsigned h3 = f2bf(r2);
;                 v4u o; o.x = h1 | (h2 << 16); o.y = h3; o.z = 0u; o.w = 0u; *(v4u*)(FS3 + ((size_t)bh * SEQ + tid * 16 + i) * 8) = o; }
;             __syncthreads();
	v_mov_b32_e32 v5, v4
	global_store_dwordx4 v[10:11], v[2:5], off offset:112
	s_nop 1
	v_add_f32_e32 v2, v22, v27
	v_mul_f32_e32 v3, 0x3fb8aa3b, v2
	v_mov_b32_e32 v240, v3
	v_xor_b32_e32 v3, 0x80000000, v3
	v_bfe_u32 v5, v3, 16, 1
	v_add3_u32 v5, v3, v5, s31
	v_and_b32_e32 v3, 0xffff0000, v5
	v_fma_f32 v2, v2, s33, -v3
	v_bfe_u32 v3, v2, 16, 1
	v_add3_u32 v3, v2, v3, s31
	v_and_b32_e32 v27, 0xffff0000, v3
	v_sub_f32_e32 v2, v2, v27
	v_bfe_u32 v3, v2, 16, 1
	v_add3_u32 v2, v2, v3, s31
	v_lshrrev_b32_e32 v3, 16, v2
	v_or_b32_sdwa v2, v27, v5 dst_sel:DWORD dst_unused:UNUSED_PAD src0_sel:DWORD src1_sel:WORD_1
	v_mov_b32_e32 v5, v4
	global_store_dwordx4 v[10:11], v[2:5], off offset:128
	s_nop 1
	v_add_f32_e32 v2, v22, v26
	v_mul_f32_e32 v3, 0x3fb8aa3b, v2
	v_mov_b32_e32 v241, v3
	v_xor_b32_e32 v3, 0x80000000, v3
	v_bfe_u32 v5, v3, 16, 1
	v_add3_u32 v5, v3, v5, s31
	v_and_b32_e32 v3, 0xffff0000, v5
	v_fma_f32 v2, v2, s33, -v3
	v_bfe_u32 v3, v2, 16, 1
	v_add3_u32 v3, v2, v3, s31
	v_and_b32_e32 v26, 0xffff0000, v3
	v_sub_f32_e32 v2, v2, v26
	v_bfe_u32 v3, v2, 16, 1
	v_add3_u32 v2, v2, v3, s31
	v_lshrrev_b32_e32 v3, 16, v2
	v_or_b32_sdwa v2, v26, v5 dst_sel:DWORD dst_unused:UNUSED_PAD src0_sel:DWORD src1_sel:WORD_1
	v_mov_b32_e32 v5, v4
	global_store_dwordx4 v[10:11], v[2:5], off offset:144
	s_nop 1
	v_add_f32_e32 v2, v22, v25
	v_mul_f32_e32 v3, 0x3fb8aa3b, v2
	v_mov_b32_e32 v242, v3
	v_xor_b32_e32 v3, 0x80000000, v3
	v_bfe_u32 v5, v3, 16, 1
	v_add3_u32 v5, v3, v5, s31
	v_and_b32_e32 v3, 0xffff0000, v5
	v_fma_f32 v2, v2, s33, -v3
	v_bfe_u32 v3, v2, 16, 1
	v_add3_u32 v3, v2, v3, s31
	v_and_b32_e32 v25, 0xffff0000, v3
	v_sub_f32_e32 v2, v2, v25
	v_bfe_u32 v3, v2, 16, 1
	v_add3_u32 v2, v2, v3, s31
	v_lshrrev_b32_e32 v3, 16, v2
	v_or_b32_sdwa v2, v25, v5 dst_sel:DWORD dst_unused:UNUSED_PAD src0_sel:DWORD src1_sel:WORD_1
	v_mov_b32_e32 v5, v4
	global_store_dwordx4 v[10:11], v[2:5], off offset:160
	s_nop 1
	v_add_f32_e32 v2, v22, v24
	v_mul_f32_e32 v3, 0x3fb8aa3b, v2
	v_mov_b32_e32 v243, v3
	global_store_dwordx4 v[8:9], v[240:243], off offset:32
	v_xor_b32_e32 v3, 0x80000000, v3
	v_bfe_u32 v5, v3, 16, 1
	v_add3_u32 v5, v3, v5, s31
	v_and_b32_e32 v3, 0xffff0000, v5
	v_fma_f32 v2, v2, s33, -v3
	v_bfe_u32 v3, v2, 16, 1
	v_add3_u32 v3, v2, v3, s31
	v_and_b32_e32 v24, 0xffff0000, v3
	v_sub_f32_e32 v2, v2, v24
	v_bfe_u32 v3, v2, 16, 1
	v_add3_u32 v2, v2, v3, s31
	v_lshrrev_b32_e32 v3, 16, v2
	v_or_b32_sdwa v2, v24, v5 dst_sel:DWORD dst_unused:UNUSED_PAD src0_sel:DWORD src1_sel:WORD_1
	v_mov_b32_e32 v5, v4
	global_store_dwordx4 v[10:11], v[2:5], off offset:176
	s_nop 1
	v_add_f32_e32 v2, v22, v23
	v_mul_f32_e32 v3, 0x3fb8aa3b, v2
	v_mov_b32_e32 v244, v3
	v_xor_b32_e32 v3, 0x80000000, v3
	v_bfe_u32 v5, v3, 16, 1
	v_add3_u32 v5, v3, v5, s31
	v_and_b32_e32 v3, 0xffff0000, v5
	v_fma_f32 v2, v2, s33, -v3
	v_bfe_u32 v3, v2, 16, 1
	v_add3_u32 v3, v2, v3, s31
	v_and_b32_e32 v23, 0xffff0000, v3
	v_sub_f32_e32 v2, v2, v23
	v_bfe_u32 v3, v2, 16, 1
	v_add3_u32 v2, v2, v3, s31
	v_lshrrev_b32_e32 v3, 16, v2
	v_or_b32_sdwa v2, v23, v5 dst_sel:DWORD dst_unused:UNUSED_PAD src0_sel:DWORD src1_sel:WORD_1
	v_mov_b32_e32 v5, v4
	global_store_dwordx4 v[10:11], v[2:5], off offset:192
	s_nop 1
	v_add_f32_e32 v2, v22, v21
	v_mul_f32_e32 v3, 0x3fb8aa3b, v2
	v_mov_b32_e32 v245, v3
	v_xor_b32_e32 v3, 0x80000000, v3
	v_bfe_u32 v5, v3, 16, 1
	v_add3_u32 v5, v3, v5, s31
	v_and_b32_e32 v3, 0xffff0000, v5
	v_fma_f32 v2, v2, s33, -v3
	v_bfe_u32 v3, v2, 16, 1
	v_add3_u32 v3, v2, v3, s31
	v_and_b32_e32 v21, 0xffff0000, v3
	v_sub_f32_e32 v2, v2, v21
	v_bfe_u32 v3, v2, 16, 1
	v_add3_u32 v2, v2, v3, s31
	v_lshrrev_b32_e32 v3, 16, v2
	v_or_b32_sdwa v2, v21, v5 dst_sel:DWORD dst_unused:UNUSED_PAD src0_sel:DWORD src1_sel:WORD_1
	v_mov_b32_e32 v5, v4
	global_store_dwordx4 v[10:11], v[2:5], off offset:208
	s_nop 1
	v_add_f32_e32 v2, v22, v20
	v_mul_f32_e32 v3, 0x3fb8aa3b, v2
	v_mov_b32_e32 v246, v3
	v_xor_b32_e32 v3, 0x80000000, v3
	v_bfe_u32 v5, v3, 16, 1
	v_add3_u32 v5, v3, v5, s31
	v_and_b32_e32 v3, 0xffff0000, v5
	v_fma_f32 v2, v2, s33, -v3
	v_bfe_u32 v3, v2, 16, 1
	v_add3_u32 v3, v2, v3, s31
	v_and_b32_e32 v20, 0xffff0000, v3
	v_sub_f32_e32 v2, v2, v20
	v_bfe_u32 v3, v2, 16, 1
	v_add3_u32 v2, v2, v3, s31
	v_lshrrev_b32_e32 v3, 16, v2
	v_or_b32_sdwa v2, v20, v5 dst_sel:DWORD dst_unused:UNUSED_PAD src0_sel:DWORD src1_sel:WORD_1
	v_mov_b32_e32 v5, v4
	global_store_dwordx4 v[10:11], v[2:5], off offset:224
	s_nop 1
	v_add_f32_e32 v2, v22, v19
	v_mul_f32_e32 v3, 0x3fb8aa3b, v2
	v_mov_b32_e32 v247, v3
	global_store_dwordx4 v[8:9], v[244:247], off offset:48
	v_xor_b32_e32 v3, 0x80000000, v3
	v_bfe_u32 v5, v3, 16, 1
	v_add3_u32 v5, v3, v5, s31
	v_and_b32_e32 v3, 0xffff0000, v5
	v_fma_f32 v2, v2, s33, -v3
	v_bfe_u32 v3, v2, 16, 1
	v_add3_u32 v3, v2, v3, s31
	v_and_b32_e32 v8, 0xffff0000, v3
	v_sub_f32_e32 v2, v2, v8
	v_bfe_u32 v3, v2, 16, 1
	v_add3_u32 v2, v2, v3, s31
	v_lshrrev_b32_e32 v3, 16, v2
	v_or_b32_sdwa v2, v8, v5 dst_sel:DWORD dst_unused:UNUSED_PAD src0_sel:DWORD src1_sel:WORD_1
	v_mov_b32_e32 v5, v4
	global_store_dwordx4 v[10:11], v[2:5], off offset:240
	s_barrier
	s_cbranch_scc1 .LBB0_243
